# grid barriers: only the XCD's last arriver writes back L2; first seam uses the same hierarchical barrier
# speedup vs baseline: 1.1517x; 1.0312x over previous
; DEV void grid_barrier(unsigned* cnt, const unsigned target, const int tid) {
;     asm volatile("s_waitcnt vmcnt(0)" ::: "memory");
;     __syncthreads();
;     if (tid == 0) {
;         __builtin_amdgcn_fence(__ATOMIC_RELEASE, "agent");
;         __hip_atomic_fetch_add(cnt, 1u, __ATOMIC_RELAXED, __HIP_MEMORY_SCOPE_AGENT);
;         while (__hip_atomic_load(cnt, __ATOMIC_RELAXED, __HIP_MEMORY_SCOPE_AGENT) < target) __builtin_amdgcn_s_sleep(28);
;         __builtin_amdgcn_fence(__ATOMIC_ACQUIRE, "agent");
;         asm volatile("s_waitcnt vmcnt(0)" ::: "memory");
;     }
;     __syncthreads();
; }
; template <int LO, int HI>
; DEV void run_phases(LAS unsigned char* lds, const int ph_lo, const int ph_hi, const int G, const int wave0, unsigned& nbar) {
;     ...
;         if (ph + 1 < ph_hi) { __syncthreads(); if (HI == 1) cg::this_grid().sync(); else { ++nbar; grid_barrier((unsigned*)(ws + WS_BAR), nbar * (unsigned)G, tid); } }
.LBB0_167:
	s_cmp_lt_i32 s65, 2
	s_cbranch_scc1 .LBB0_179
	v_lshrrev_b32_e32 v2, 20, v0
	v_lshrrev_b32_e32 v0, 10, v0
	v_or_b32_e32 v0, v0, v2
	s_movk_i32 s2, 0x3ff
	v_and_or_b32 v0, v0, s2, v1
	v_cmp_eq_u32_e32 vcc, 0, v0
	s_waitcnt vmcnt(0)
	s_barrier
	s_barrier
	s_and_saveexec_b64 s[2:3], vcc
	s_cbranch_execz .LBB0_178
	v_readlane_b32 s4, v251, 2
	v_readlane_b32 s5, v251, 3
	v_readlane_b32 s6, v251, 1
	s_mov_b32 s7, 1
	s_getreg_b32 s8, hwreg(HW_REG_XCC_ID, 0, 4)
	s_load_dwordx2 s[4:5], s[4:5], 0x110
	s_lshr_b32 s6, s6, 3
	s_mul_i32 s6, s6, s7
	s_lshl_b32 s9, s7, 3
	s_lshl_b32 s8, s8, 2
	s_add_u32 s8, s8, 0xa0
	v_mov_b32_e32 v3, 1
	v_mov_b32_e32 v2, s8
	v_mov_b32_e32 v5, 0
	s_waitcnt lgkmcnt(0)
	s_add_u32 s4, s4, 0x300020
	s_addc_u32 s5, s5, 0
	global_atomic_add v4, v2, v3, s[4:5] sc0
	s_waitcnt vmcnt(0)
	v_add_u32_e32 v4, 1, v4
	v_cmp_eq_u32_e32 vcc, s6, v4
	s_cbranch_vccz .Lgb0_follow
	buffer_wbl2 sc1
	s_waitcnt vmcnt(0)
	global_atomic_add v5, v3, s[4:5]
.Lgb0_ptop:
	global_load_dword v4, v5, s[4:5] sc1
	s_waitcnt vmcnt(0)
	v_cmp_gt_u32_e32 vcc, s9, v4
	s_cbranch_vccz .Lgb0_tdone
	s_sleep 28
	s_branch .Lgb0_ptop
.Lgb0_tdone:
	v_mov_b32_e32 v4, s7
	global_store_dword v2, v4, s[4:5] offset:32
	s_branch .Lgb0_done
.Lgb0_follow:
	global_load_dword v4, v2, s[4:5] offset:32 sc1
	s_waitcnt vmcnt(0)
	v_cmp_gt_u32_e32 vcc, s7, v4
	s_cbranch_vccz .Lgb0_done
	s_sleep 8
	s_branch .Lgb0_follow
.Lgb0_done:
.LBB0_177:
	buffer_inv sc1
.LBB0_178:
	s_or_b64 exec, exec, s[2:3]
	s_barrier

; DEV void grid_barrier(unsigned* cnt, const unsigned target, const int tid) {
;     asm volatile("s_waitcnt vmcnt(0)" ::: "memory");
;     __syncthreads();
;     if (tid == 0) {
;         __builtin_amdgcn_fence(__ATOMIC_RELEASE, "agent");
;         __hip_atomic_fetch_add(cnt, 1u, __ATOMIC_RELAXED, __HIP_MEMORY_SCOPE_AGENT);
;         while (__hip_atomic_load(cnt, __ATOMIC_RELAXED, __HIP_MEMORY_SCOPE_AGENT) < target) __builtin_amdgcn_s_sleep(28);
;         __builtin_amdgcn_fence(__ATOMIC_ACQUIRE, "agent");
;         asm volatile("s_waitcnt vmcnt(0)" ::: "memory");
;     }
;     __syncthreads();
; }
; template <int LO, int HI>
; DEV void run_phases(LAS unsigned char* lds, const int ph_lo, const int ph_hi, const int G, const int wave0, unsigned& nbar) {
;     ...
;             if (ph_lo < ph) { ++nbar; grid_barrier((unsigned*)(ws + WS_BAR), nbar * (unsigned)G, tid); }
.LBB0_198:
	s_or_b64 exec, exec, s[12:13]
	v_readlane_b32 s2, v251, 12
	v_readlane_b32 s3, v251, 13
	s_andn2_b64 vcc, exec, s[2:3]
	s_cbranch_vccnz .LBB0_206
	s_waitcnt vmcnt(0)
	v_readlane_b32 s2, v251, 5
	s_add_i32 s2, s2, 1
	v_cmp_eq_u32_e32 vcc, 0, v155
	v_writelane_b32 v251, s2, 5
	s_barrier
	s_and_saveexec_b64 s[2:3], vcc
	s_cbranch_execz .LBB0_205
	v_readlane_b32 s4, v251, 2
	v_readlane_b32 s5, v251, 3
	v_readlane_b32 s6, v251, 1
	v_readlane_b32 s7, v251, 5
	s_getreg_b32 s12, hwreg(HW_REG_XCC_ID, 0, 4)
	s_load_dwordx2 s[4:5], s[4:5], 0x110
	s_lshr_b32 s6, s6, 3
	s_mul_i32 s6, s6, s7
	s_lshl_b32 s13, s7, 3
	s_lshl_b32 s12, s12, 2
	s_add_u32 s12, s12, 0x40
	v_mov_b32_e32 v3, 1
	v_mov_b32_e32 v2, s12
	v_mov_b32_e32 v5, 0
	s_waitcnt lgkmcnt(0)
	s_add_u32 s4, s4, 0x300000
	s_addc_u32 s5, s5, 0
	global_atomic_add v4, v2, v3, s[4:5] sc0
	s_waitcnt vmcnt(0)
	v_add_u32_e32 v4, 1, v4
	v_cmp_eq_u32_e32 vcc, s6, v4
	s_cbranch_vccz .Lgb1_follow
	buffer_wbl2 sc1
	s_waitcnt vmcnt(0)
	global_atomic_add v5, v3, s[4:5]

; DEV void grid_barrier(unsigned* cnt, const unsigned target, const int tid) {
;     asm volatile("s_waitcnt vmcnt(0)" ::: "memory");
;     __syncthreads();
;     if (tid == 0) {
;         __builtin_amdgcn_fence(__ATOMIC_RELEASE, "agent");
;         __hip_atomic_fetch_add(cnt, 1u, __ATOMIC_RELAXED, __HIP_MEMORY_SCOPE_AGENT);
;         while (__hip_atomic_load(cnt, __ATOMIC_RELAXED, __HIP_MEMORY_SCOPE_AGENT) < target) __builtin_amdgcn_s_sleep(28);
;         __builtin_amdgcn_fence(__ATOMIC_ACQUIRE, "agent");
;         asm volatile("s_waitcnt vmcnt(0)" ::: "memory");
;     }
;     __syncthreads();
; }
; template <int LO, int HI>
; DEV void run_phases(LAS unsigned char* lds, const int ph_lo, const int ph_hi, const int G, const int wave0, unsigned& nbar) {
;     ...
;         if (ph + 1 < ph_hi) { __syncthreads(); if (HI == 1) cg::this_grid().sync(); else { ++nbar; grid_barrier((unsigned*)(ws + WS_BAR), nbar * (unsigned)G, tid); } }
.LBB0_1358:
	v_readlane_b32 s2, v251, 7
	s_add_i32 s0, s77, 1
	v_readlane_b32 s3, v251, 8
	s_cmp_ge_i32 s0, s3
	s_cbranch_scc1 .LBB0_1366
	s_barrier
	s_waitcnt vmcnt(0)
	v_readlane_b32 s0, v251, 5
	s_add_i32 s0, s0, 1
	v_cmp_eq_u32_e32 vcc, 0, v130
	v_writelane_b32 v251, s0, 5
	s_barrier
	s_and_saveexec_b64 s[0:1], vcc
	s_cbranch_execz .LBB0_1365
	v_readlane_b32 s2, v251, 2
	v_readlane_b32 s3, v251, 3
	v_readlane_b32 s4, v251, 1
	v_readlane_b32 s5, v251, 5
	s_getreg_b32 s6, hwreg(HW_REG_XCC_ID, 0, 4)
	s_load_dwordx2 s[2:3], s[2:3], 0x110
	s_lshr_b32 s4, s4, 3
	s_mul_i32 s4, s4, s5
	s_lshl_b32 s7, s5, 3
	s_lshl_b32 s6, s6, 2
	s_add_u32 s6, s6, 0x40
	v_mov_b32_e32 v3, 1
	v_mov_b32_e32 v2, s6
	v_mov_b32_e32 v5, 0
	s_waitcnt lgkmcnt(0)
	s_add_u32 s2, s2, 0x300000
	s_addc_u32 s3, s3, 0
	global_atomic_add v4, v2, v3, s[2:3] sc0
	s_waitcnt vmcnt(0)
	v_add_u32_e32 v4, 1, v4
	v_cmp_eq_u32_e32 vcc, s4, v4
	s_cbranch_vccz .Lgb2_follow
	buffer_wbl2 sc1
	s_waitcnt vmcnt(0)
	global_atomic_add v5, v3, s[2:3]

; DEV void grid_barrier(unsigned* cnt, const unsigned target, const int tid) {
;     asm volatile("s_waitcnt vmcnt(0)" ::: "memory");
;     __syncthreads();
;     if (tid == 0) {
;         __builtin_amdgcn_fence(__ATOMIC_RELEASE, "agent");
;         __hip_atomic_fetch_add(cnt, 1u, __ATOMIC_RELAXED, __HIP_MEMORY_SCOPE_AGENT);
;         while (__hip_atomic_load(cnt, __ATOMIC_RELAXED, __HIP_MEMORY_SCOPE_AGENT) < target) __builtin_amdgcn_s_sleep(28);
;         __builtin_amdgcn_fence(__ATOMIC_ACQUIRE, "agent");
;         asm volatile("s_waitcnt vmcnt(0)" ::: "memory");
;     }
;     __syncthreads();
; }
; template <int LO, int HI>
; DEV void run_phases(LAS unsigned char* lds, const int ph_lo, const int ph_hi, const int G, const int wave0, unsigned& nbar) {
;     ...
;             if (ph_lo < ph) { ++nbar; grid_barrier((unsigned*)(ws + WS_BAR), nbar * (unsigned)G, tid); }
.LBB0_1396:
	s_or_b64 exec, exec, s[0:1]
	v_readlane_b32 s0, v251, 20
	v_readlane_b32 s1, v251, 21
	s_andn2_b64 vcc, exec, s[0:1]
	s_cbranch_vccnz .LBB0_1404
	s_waitcnt vmcnt(0)
	v_readlane_b32 s0, v251, 5
	s_add_i32 s0, s0, 1
	v_cmp_eq_u32_e32 vcc, 0, v172
	v_writelane_b32 v251, s0, 5
	s_barrier
	s_and_saveexec_b64 s[0:1], vcc
	s_cbranch_execz .LBB0_1403
	v_readlane_b32 s2, v251, 2
	v_readlane_b32 s3, v251, 3
	v_readlane_b32 s4, v251, 1
	v_readlane_b32 s5, v251, 5
	s_getreg_b32 s6, hwreg(HW_REG_XCC_ID, 0, 4)
	s_load_dwordx2 s[2:3], s[2:3], 0x110
	s_lshr_b32 s4, s4, 3
	s_mul_i32 s4, s4, s5
	s_lshl_b32 s7, s5, 3
	s_lshl_b32 s6, s6, 2
	s_add_u32 s6, s6, 0x40
	v_mov_b32_e32 v3, 1
	v_mov_b32_e32 v2, s6
	v_mov_b32_e32 v5, 0
	s_waitcnt lgkmcnt(0)
	s_add_u32 s2, s2, 0x300000
	s_addc_u32 s3, s3, 0
	global_atomic_add v4, v2, v3, s[2:3] sc0
	s_waitcnt vmcnt(0)
	v_add_u32_e32 v4, 1, v4
	v_cmp_eq_u32_e32 vcc, s4, v4
	s_cbranch_vccz .Lgb3_follow
	buffer_wbl2 sc1
	s_waitcnt vmcnt(0)
	global_atomic_add v5, v3, s[2:3]

; DEV void grid_barrier(unsigned* cnt, const unsigned target, const int tid) {
;     asm volatile("s_waitcnt vmcnt(0)" ::: "memory");
;     __syncthreads();
;     if (tid == 0) {
;         __builtin_amdgcn_fence(__ATOMIC_RELEASE, "agent");
;         __hip_atomic_fetch_add(cnt, 1u, __ATOMIC_RELAXED, __HIP_MEMORY_SCOPE_AGENT);
;         while (__hip_atomic_load(cnt, __ATOMIC_RELAXED, __HIP_MEMORY_SCOPE_AGENT) < target) __builtin_amdgcn_s_sleep(28);
;         __builtin_amdgcn_fence(__ATOMIC_ACQUIRE, "agent");
;         asm volatile("s_waitcnt vmcnt(0)" ::: "memory");
;     }
;     __syncthreads();
; }
; template <int LO, int HI>
; DEV void run_phases(LAS unsigned char* lds, const int ph_lo, const int ph_hi, const int G, const int wave0, unsigned& nbar) {
;     ...
;         if (ph + 1 < ph_hi) { __syncthreads(); if (HI == 1) cg::this_grid().sync(); else { ++nbar; grid_barrier((unsigned*)(ws + WS_BAR), nbar * (unsigned)G, tid); } }
.LBB0_2200:
	v_readlane_b32 s2, v251, 7
	s_add_i32 s0, s82, 1
	v_readlane_b32 s3, v251, 8
	s_cmp_ge_i32 s0, s3
	s_cbranch_scc1 .LBB0_1374
	s_waitcnt lgkmcnt(0)
	s_barrier
	s_waitcnt vmcnt(0)
	v_readlane_b32 s0, v251, 5
	s_add_i32 s0, s0, 1
	v_cmp_eq_u32_e32 vcc, 0, v131
	v_writelane_b32 v251, s0, 5
	s_barrier
	s_and_saveexec_b64 s[0:1], vcc
	s_cbranch_execz .LBB0_1373
	v_readlane_b32 s2, v251, 2
	v_readlane_b32 s3, v251, 3
	v_readlane_b32 s4, v251, 1
	v_readlane_b32 s5, v251, 5
	s_getreg_b32 s6, hwreg(HW_REG_XCC_ID, 0, 4)
	s_load_dwordx2 s[2:3], s[2:3], 0x110
	s_lshr_b32 s4, s4, 3
	s_mul_i32 s4, s4, s5
	s_lshl_b32 s7, s5, 3
	s_lshl_b32 s6, s6, 2
	s_add_u32 s6, s6, 0x40
	v_mov_b32_e32 v3, 1
	v_mov_b32_e32 v2, s6
	v_mov_b32_e32 v5, 0
	s_waitcnt lgkmcnt(0)
	s_add_u32 s2, s2, 0x300000
	s_addc_u32 s3, s3, 0
	global_atomic_add v4, v2, v3, s[2:3] sc0
	s_waitcnt vmcnt(0)
	v_add_u32_e32 v4, 1, v4
	v_cmp_eq_u32_e32 vcc, s4, v4
	s_cbranch_vccz .Lgb4_follow
	buffer_wbl2 sc1
	s_waitcnt vmcnt(0)
	global_atomic_add v5, v3, s[2:3]
